# stick-breaking attention loop: static s_setprio 1 for the younger wave half (waves 4-7)
# baseline (speedup 1.0000x reference)
; #define LAS __attribute__((address_space(3)))
; __device__ __forceinline__ void sb_attn_phase(int j, LAS unsigned char* lds, unsigned* ctr) {
;     ...
;         for (;; --t) {
;             *(LAS u32x4*)kdst = kr; *(LAS u32x4*)vdst = vr;
;             __syncthreads();
;             if (t > 0) { kr = *(const u32x4*)(Kb + (rowb + 64 * (t - 1) + lkv) * 1024 + h * 64 + lch * 8); vr = *(const u32x4*)(Vb + (rowb + 64 * (t - 1) + lkv) * 1024 + h * 64 + lch * 8); }
;             if (t <= my_top && !wdone) { sb_tile(L, qf, 64 * t, qpos, lane, carry, o); wdone = __all(carry < -SB_THR); }
.LBB0_294:
	v_cmp_gt_i32_e32 vcc, 1, v105
	s_and_b64 vcc, exec, vcc
	s_waitcnt vmcnt(1)
	ds_write_b128 v138, v[80:83]
	s_waitcnt vmcnt(0)
	ds_write_b128 v139, v[84:87] offset:18432
	s_waitcnt lgkmcnt(0)
	s_barrier
	v_readlane_b32 s10, v252, 17
	s_cmp_lt_u32 s10, 4
	s_cbranch_scc1 .Lsb_noprio
	s_setprio 1
.Lsb_noprio:
	s_cbranch_vccnz .LBB0_296
	v_lshl_add_u64 v[34:35], v[114:115], 0, s[90:91]
	v_lshlrev_b64 v[34:35], 11, v[34:35]
	v_lshl_add_u64 v[36:37], v[112:113], 0, v[34:35]
	v_lshl_add_u64 v[34:35], v[110:111], 0, v[34:35]
	global_load_dwordx4 v[80:83], v[34:35], off
	global_load_dwordx4 v[84:87], v[36:37], off
